# P6 SwiGLU epilogue hand-rewritten on packed f32 pairs (same op order), no register shuffles, SADDR addressing; plus earlier fixes
# speedup vs baseline: 1.0102x; 1.0007x over previous
.LBB0_844:
	v_lshl_add_u32 v148, s18, 8, v1
	v_lshl_or_b32 v174, s16, 7, v143
	v_mul_u32_u24_e32 v149, 0x1600, v148
	v_lshlrev_b32_e32 v148, 2, v148
	v_lshl_add_u32 v149, v174, 1, v149
	global_load_dword v151, v148, s[76:77]
	global_load_dword v153, v148, s[76:77] offset:64
	global_load_dword v155, v148, s[76:77] offset:128
	global_load_dword v157, v148, s[76:77] offset:192
	global_load_dword v159, v148, s[76:77] offset:512
	global_load_dword v161, v148, s[76:77] offset:576
	global_load_dword v163, v148, s[76:77] offset:640
	global_load_dword v165, v148, s[76:77] offset:704
	s_mov_b32 s20, 0xbfb8aa3b
	s_mov_b32 s21, 0xbfb8aa3b
	s_waitcnt vmcnt(0)
	v_fmamk_f32 v150, v151, 0x3a800000, v147
	v_fmamk_f32 v152, v153, 0x3a800000, v147
	v_fmamk_f32 v154, v155, 0x3a800000, v147
	v_fmamk_f32 v156, v157, 0x3a800000, v147
	v_fmamk_f32 v158, v159, 0x3a800000, v147
	v_fmamk_f32 v160, v161, 0x3a800000, v147
	v_fmamk_f32 v162, v163, 0x3a800000, v147
	v_fmamk_f32 v164, v165, 0x3a800000, v147
	v_rsq_f32_e32 v150, v150
	v_rsq_f32_e32 v152, v152
	v_rsq_f32_e32 v154, v154
	v_rsq_f32_e32 v156, v156
	v_rsq_f32_e32 v158, v158
	v_rsq_f32_e32 v160, v160
	v_rsq_f32_e32 v162, v162
	v_rsq_f32_e32 v164, v164
	v_pk_mul_f32 v[126:127], v[126:127], v[150:151] op_sel_hi:[1,0]
	v_pk_mul_f32 v[128:129], v[128:129], v[150:151] op_sel_hi:[1,0]
	v_pk_mul_f32 v[122:123], v[122:123], v[150:151] op_sel_hi:[1,0]
	v_pk_mul_f32 v[124:125], v[124:125], v[150:151] op_sel_hi:[1,0]
	v_pk_mul_f32 v[118:119], v[118:119], v[150:151] op_sel_hi:[1,0]
	v_pk_mul_f32 v[120:121], v[120:121], v[150:151] op_sel_hi:[1,0]
	v_pk_mul_f32 v[114:115], v[114:115], v[150:151] op_sel_hi:[1,0]
	v_pk_mul_f32 v[116:117], v[116:117], v[150:151] op_sel_hi:[1,0]
	v_pk_mul_f32 v[166:167], v[126:127], s[20:21]
	v_pk_mul_f32 v[168:169], v[128:129], s[20:21]
	v_pk_mul_f32 v[170:171], v[122:123], s[20:21]
	v_pk_mul_f32 v[172:173], v[124:125], s[20:21]
	v_exp_f32_e32 v166, v166
	v_exp_f32_e32 v167, v167
	v_exp_f32_e32 v168, v168
	v_exp_f32_e32 v169, v169
	v_exp_f32_e32 v170, v170
	v_exp_f32_e32 v171, v171
	v_exp_f32_e32 v172, v172
	v_exp_f32_e32 v173, v173
	v_pk_add_f32 v[166:167], v[166:167], 1.0 op_sel_hi:[1,0]
	v_pk_add_f32 v[168:169], v[168:169], 1.0 op_sel_hi:[1,0]
	v_pk_add_f32 v[170:171], v[170:171], 1.0 op_sel_hi:[1,0]
	v_pk_add_f32 v[172:173], v[172:173], 1.0 op_sel_hi:[1,0]
	v_rcp_f32_e32 v166, v166
	v_rcp_f32_e32 v167, v167
	v_rcp_f32_e32 v168, v168
	v_rcp_f32_e32 v169, v169
	v_rcp_f32_e32 v170, v170
	v_rcp_f32_e32 v171, v171
	v_rcp_f32_e32 v172, v172
	v_rcp_f32_e32 v173, v173
	v_pk_mul_f32 v[126:127], v[126:127], v[118:119]
	v_pk_mul_f32 v[128:129], v[128:129], v[120:121]
	v_pk_mul_f32 v[122:123], v[122:123], v[114:115]
	v_pk_mul_f32 v[124:125], v[124:125], v[116:117]
	v_pk_mul_f32 v[126:127], v[126:127], v[166:167]
	v_pk_mul_f32 v[128:129], v[128:129], v[168:169]
	v_pk_mul_f32 v[122:123], v[122:123], v[170:171]
	v_pk_mul_f32 v[124:125], v[124:125], v[172:173]
	v_cvt_pk_bf16_f32 v126, v126, v127
	v_cvt_pk_bf16_f32 v127, v128, v129
	v_cvt_pk_bf16_f32 v128, v122, v123
	v_cvt_pk_bf16_f32 v129, v124, v125
	global_store_dwordx4 v149, v[126:129], s[92:93]
	v_pk_mul_f32 v[110:111], v[110:111], v[152:153] op_sel_hi:[1,0]
	v_pk_mul_f32 v[112:113], v[112:113], v[152:153] op_sel_hi:[1,0]
	v_pk_mul_f32 v[102:103], v[102:103], v[152:153] op_sel_hi:[1,0]
	v_pk_mul_f32 v[104:105], v[104:105], v[152:153] op_sel_hi:[1,0]
	v_pk_mul_f32 v[106:107], v[106:107], v[152:153] op_sel_hi:[1,0]
	v_pk_mul_f32 v[108:109], v[108:109], v[152:153] op_sel_hi:[1,0]
	v_pk_mul_f32 v[98:99], v[98:99], v[152:153] op_sel_hi:[1,0]
	v_pk_mul_f32 v[100:101], v[100:101], v[152:153] op_sel_hi:[1,0]
	v_pk_mul_f32 v[166:167], v[110:111], s[20:21]
	v_pk_mul_f32 v[168:169], v[112:113], s[20:21]
	v_pk_mul_f32 v[170:171], v[102:103], s[20:21]
	v_pk_mul_f32 v[172:173], v[104:105], s[20:21]
	v_exp_f32_e32 v166, v166
	v_exp_f32_e32 v167, v167
	v_exp_f32_e32 v168, v168
	v_exp_f32_e32 v169, v169
	v_exp_f32_e32 v170, v170
	v_exp_f32_e32 v171, v171
	v_exp_f32_e32 v172, v172
	v_exp_f32_e32 v173, v173
	v_pk_add_f32 v[166:167], v[166:167], 1.0 op_sel_hi:[1,0]
	v_pk_add_f32 v[168:169], v[168:169], 1.0 op_sel_hi:[1,0]
	v_pk_add_f32 v[170:171], v[170:171], 1.0 op_sel_hi:[1,0]
	v_pk_add_f32 v[172:173], v[172:173], 1.0 op_sel_hi:[1,0]
	v_rcp_f32_e32 v166, v166
	v_rcp_f32_e32 v167, v167
	v_rcp_f32_e32 v168, v168
	v_rcp_f32_e32 v169, v169
	v_rcp_f32_e32 v170, v170
	v_rcp_f32_e32 v171, v171
	v_rcp_f32_e32 v172, v172
	v_rcp_f32_e32 v173, v173
	v_pk_mul_f32 v[110:111], v[110:111], v[106:107]
	v_pk_mul_f32 v[112:113], v[112:113], v[108:109]
	v_pk_mul_f32 v[102:103], v[102:103], v[98:99]
	v_pk_mul_f32 v[104:105], v[104:105], v[100:101]
	v_pk_mul_f32 v[110:111], v[110:111], v[166:167]
	v_pk_mul_f32 v[112:113], v[112:113], v[168:169]
	v_pk_mul_f32 v[102:103], v[102:103], v[170:171]
	v_pk_mul_f32 v[104:105], v[104:105], v[172:173]
	v_cvt_pk_bf16_f32 v110, v110, v111
	v_cvt_pk_bf16_f32 v111, v112, v113
	v_cvt_pk_bf16_f32 v112, v102, v103
	v_cvt_pk_bf16_f32 v113, v104, v105
	v_add_u32_e32 v174, 0x16000, v149
	global_store_dwordx4 v174, v[110:113], s[92:93]
	v_pk_mul_f32 v[94:95], v[94:95], v[154:155] op_sel_hi:[1,0]
	v_pk_mul_f32 v[96:97], v[96:97], v[154:155] op_sel_hi:[1,0]
	v_pk_mul_f32 v[86:87], v[86:87], v[154:155] op_sel_hi:[1,0]
	v_pk_mul_f32 v[88:89], v[88:89], v[154:155] op_sel_hi:[1,0]
	v_pk_mul_f32 v[90:91], v[90:91], v[154:155] op_sel_hi:[1,0]
	v_pk_mul_f32 v[92:93], v[92:93], v[154:155] op_sel_hi:[1,0]
	v_pk_mul_f32 v[82:83], v[82:83], v[154:155] op_sel_hi:[1,0]
	v_pk_mul_f32 v[84:85], v[84:85], v[154:155] op_sel_hi:[1,0]
	v_pk_mul_f32 v[166:167], v[94:95], s[20:21]
	v_pk_mul_f32 v[168:169], v[96:97], s[20:21]
	v_pk_mul_f32 v[170:171], v[86:87], s[20:21]
	v_pk_mul_f32 v[172:173], v[88:89], s[20:21]
	v_exp_f32_e32 v166, v166
	v_exp_f32_e32 v167, v167
	v_exp_f32_e32 v168, v168
	v_exp_f32_e32 v169, v169
	v_exp_f32_e32 v170, v170
	v_exp_f32_e32 v171, v171
	v_exp_f32_e32 v172, v172
	v_exp_f32_e32 v173, v173
	v_pk_add_f32 v[166:167], v[166:167], 1.0 op_sel_hi:[1,0]
	v_pk_add_f32 v[168:169], v[168:169], 1.0 op_sel_hi:[1,0]
	v_pk_add_f32 v[170:171], v[170:171], 1.0 op_sel_hi:[1,0]
	v_pk_add_f32 v[172:173], v[172:173], 1.0 op_sel_hi:[1,0]
	v_rcp_f32_e32 v166, v166
	v_rcp_f32_e32 v167, v167
	v_rcp_f32_e32 v168, v168
	v_rcp_f32_e32 v169, v169
	v_rcp_f32_e32 v170, v170
	v_rcp_f32_e32 v171, v171
	v_rcp_f32_e32 v172, v172
	v_rcp_f32_e32 v173, v173
	v_pk_mul_f32 v[94:95], v[94:95], v[90:91]
	v_pk_mul_f32 v[96:97], v[96:97], v[92:93]
	v_pk_mul_f32 v[86:87], v[86:87], v[82:83]
	v_pk_mul_f32 v[88:89], v[88:89], v[84:85]
	v_pk_mul_f32 v[94:95], v[94:95], v[166:167]
	v_pk_mul_f32 v[96:97], v[96:97], v[168:169]
	v_pk_mul_f32 v[86:87], v[86:87], v[170:171]
	v_pk_mul_f32 v[88:89], v[88:89], v[172:173]
	v_cvt_pk_bf16_f32 v94, v94, v95
	v_cvt_pk_bf16_f32 v95, v96, v97
	v_cvt_pk_bf16_f32 v96, v86, v87
	v_cvt_pk_bf16_f32 v97, v88, v89
	v_add_u32_e32 v174, 0x2c000, v149
	global_store_dwordx4 v174, v[94:97], s[92:93]
	v_pk_mul_f32 v[78:79], v[78:79], v[156:157] op_sel_hi:[1,0]
	v_pk_mul_f32 v[80:81], v[80:81], v[156:157] op_sel_hi:[1,0]
	v_pk_mul_f32 v[70:71], v[70:71], v[156:157] op_sel_hi:[1,0]
	v_pk_mul_f32 v[72:73], v[72:73], v[156:157] op_sel_hi:[1,0]
	v_pk_mul_f32 v[74:75], v[74:75], v[156:157] op_sel_hi:[1,0]
	v_pk_mul_f32 v[76:77], v[76:77], v[156:157] op_sel_hi:[1,0]
	v_pk_mul_f32 v[66:67], v[66:67], v[156:157] op_sel_hi:[1,0]
	v_pk_mul_f32 v[68:69], v[68:69], v[156:157] op_sel_hi:[1,0]
	v_pk_mul_f32 v[166:167], v[78:79], s[20:21]
	v_pk_mul_f32 v[168:169], v[80:81], s[20:21]
	v_pk_mul_f32 v[170:171], v[70:71], s[20:21]
	v_pk_mul_f32 v[172:173], v[72:73], s[20:21]
	v_exp_f32_e32 v166, v166
	v_exp_f32_e32 v167, v167
	v_exp_f32_e32 v168, v168
	v_exp_f32_e32 v169, v169
	v_exp_f32_e32 v170, v170
	v_exp_f32_e32 v171, v171
	v_exp_f32_e32 v172, v172
	v_exp_f32_e32 v173, v173
	v_pk_add_f32 v[166:167], v[166:167], 1.0 op_sel_hi:[1,0]
	v_pk_add_f32 v[168:169], v[168:169], 1.0 op_sel_hi:[1,0]
	v_pk_add_f32 v[170:171], v[170:171], 1.0 op_sel_hi:[1,0]
	v_pk_add_f32 v[172:173], v[172:173], 1.0 op_sel_hi:[1,0]
	v_rcp_f32_e32 v166, v166
	v_rcp_f32_e32 v167, v167
	v_rcp_f32_e32 v168, v168
	v_rcp_f32_e32 v169, v169
	v_rcp_f32_e32 v170, v170
	v_rcp_f32_e32 v171, v171
	v_rcp_f32_e32 v172, v172
	v_rcp_f32_e32 v173, v173
	v_pk_mul_f32 v[78:79], v[78:79], v[74:75]
	v_pk_mul_f32 v[80:81], v[80:81], v[76:77]
	v_pk_mul_f32 v[70:71], v[70:71], v[66:67]
	v_pk_mul_f32 v[72:73], v[72:73], v[68:69]
	v_pk_mul_f32 v[78:79], v[78:79], v[166:167]
	v_pk_mul_f32 v[80:81], v[80:81], v[168:169]
	v_pk_mul_f32 v[70:71], v[70:71], v[170:171]
	v_pk_mul_f32 v[72:73], v[72:73], v[172:173]
	v_cvt_pk_bf16_f32 v78, v78, v79
	v_cvt_pk_bf16_f32 v79, v80, v81
	v_cvt_pk_bf16_f32 v80, v70, v71
	v_cvt_pk_bf16_f32 v81, v72, v73
	v_add_u32_e32 v174, 0x42000, v149
	global_store_dwordx4 v174, v[78:81], s[92:93]
	v_pk_mul_f32 v[62:63], v[62:63], v[158:159] op_sel_hi:[1,0]
	v_pk_mul_f32 v[64:65], v[64:65], v[158:159] op_sel_hi:[1,0]
	v_pk_mul_f32 v[54:55], v[54:55], v[158:159] op_sel_hi:[1,0]
	v_pk_mul_f32 v[56:57], v[56:57], v[158:159] op_sel_hi:[1,0]
	v_pk_mul_f32 v[58:59], v[58:59], v[158:159] op_sel_hi:[1,0]
	v_pk_mul_f32 v[60:61], v[60:61], v[158:159] op_sel_hi:[1,0]
	v_pk_mul_f32 v[50:51], v[50:51], v[158:159] op_sel_hi:[1,0]
	v_pk_mul_f32 v[52:53], v[52:53], v[158:159] op_sel_hi:[1,0]
	v_pk_mul_f32 v[166:167], v[62:63], s[20:21]
	v_pk_mul_f32 v[168:169], v[64:65], s[20:21]
	v_pk_mul_f32 v[170:171], v[54:55], s[20:21]
	v_pk_mul_f32 v[172:173], v[56:57], s[20:21]
	v_exp_f32_e32 v166, v166
	v_exp_f32_e32 v167, v167
	v_exp_f32_e32 v168, v168
	v_exp_f32_e32 v169, v169
	v_exp_f32_e32 v170, v170
	v_exp_f32_e32 v171, v171
	v_exp_f32_e32 v172, v172
	v_exp_f32_e32 v173, v173
	v_pk_add_f32 v[166:167], v[166:167], 1.0 op_sel_hi:[1,0]
	v_pk_add_f32 v[168:169], v[168:169], 1.0 op_sel_hi:[1,0]
	v_pk_add_f32 v[170:171], v[170:171], 1.0 op_sel_hi:[1,0]
	v_pk_add_f32 v[172:173], v[172:173], 1.0 op_sel_hi:[1,0]
	v_rcp_f32_e32 v166, v166
	v_rcp_f32_e32 v167, v167
	v_rcp_f32_e32 v168, v168
	v_rcp_f32_e32 v169, v169
	v_rcp_f32_e32 v170, v170
	v_rcp_f32_e32 v171, v171
	v_rcp_f32_e32 v172, v172
	v_rcp_f32_e32 v173, v173
	v_pk_mul_f32 v[62:63], v[62:63], v[58:59]
	v_pk_mul_f32 v[64:65], v[64:65], v[60:61]
	v_pk_mul_f32 v[54:55], v[54:55], v[50:51]
	v_pk_mul_f32 v[56:57], v[56:57], v[52:53]
	v_pk_mul_f32 v[62:63], v[62:63], v[166:167]
	v_pk_mul_f32 v[64:65], v[64:65], v[168:169]
	v_pk_mul_f32 v[54:55], v[54:55], v[170:171]
	v_pk_mul_f32 v[56:57], v[56:57], v[172:173]
	v_cvt_pk_bf16_f32 v62, v62, v63
	v_cvt_pk_bf16_f32 v63, v64, v65
	v_cvt_pk_bf16_f32 v64, v54, v55
	v_cvt_pk_bf16_f32 v65, v56, v57
	v_add_u32_e32 v174, 0xb0000, v149
	global_store_dwordx4 v174, v[62:65], s[92:93]
	v_pk_mul_f32 v[46:47], v[46:47], v[160:161] op_sel_hi:[1,0]
	v_pk_mul_f32 v[48:49], v[48:49], v[160:161] op_sel_hi:[1,0]
	v_pk_mul_f32 v[38:39], v[38:39], v[160:161] op_sel_hi:[1,0]
	v_pk_mul_f32 v[40:41], v[40:41], v[160:161] op_sel_hi:[1,0]
	v_pk_mul_f32 v[42:43], v[42:43], v[160:161] op_sel_hi:[1,0]
	v_pk_mul_f32 v[44:45], v[44:45], v[160:161] op_sel_hi:[1,0]
	v_pk_mul_f32 v[34:35], v[34:35], v[160:161] op_sel_hi:[1,0]
	v_pk_mul_f32 v[36:37], v[36:37], v[160:161] op_sel_hi:[1,0]
	v_pk_mul_f32 v[166:167], v[46:47], s[20:21]
	v_pk_mul_f32 v[168:169], v[48:49], s[20:21]
	v_pk_mul_f32 v[170:171], v[38:39], s[20:21]
	v_pk_mul_f32 v[172:173], v[40:41], s[20:21]
	v_exp_f32_e32 v166, v166
	v_exp_f32_e32 v167, v167
	v_exp_f32_e32 v168, v168
	v_exp_f32_e32 v169, v169
	v_exp_f32_e32 v170, v170
	v_exp_f32_e32 v171, v171
	v_exp_f32_e32 v172, v172
	v_exp_f32_e32 v173, v173
	v_pk_add_f32 v[166:167], v[166:167], 1.0 op_sel_hi:[1,0]
	v_pk_add_f32 v[168:169], v[168:169], 1.0 op_sel_hi:[1,0]
	v_pk_add_f32 v[170:171], v[170:171], 1.0 op_sel_hi:[1,0]
	v_pk_add_f32 v[172:173], v[172:173], 1.0 op_sel_hi:[1,0]
	v_rcp_f32_e32 v166, v166
	v_rcp_f32_e32 v167, v167
	v_rcp_f32_e32 v168, v168
	v_rcp_f32_e32 v169, v169
	v_rcp_f32_e32 v170, v170
	v_rcp_f32_e32 v171, v171
	v_rcp_f32_e32 v172, v172
	v_rcp_f32_e32 v173, v173
	v_pk_mul_f32 v[46:47], v[46:47], v[42:43]
	v_pk_mul_f32 v[48:49], v[48:49], v[44:45]
	v_pk_mul_f32 v[38:39], v[38:39], v[34:35]
	v_pk_mul_f32 v[40:41], v[40:41], v[36:37]
	v_pk_mul_f32 v[46:47], v[46:47], v[166:167]
	v_pk_mul_f32 v[48:49], v[48:49], v[168:169]
	v_pk_mul_f32 v[38:39], v[38:39], v[170:171]
	v_pk_mul_f32 v[40:41], v[40:41], v[172:173]
	v_cvt_pk_bf16_f32 v46, v46, v47
	v_cvt_pk_bf16_f32 v47, v48, v49
	v_cvt_pk_bf16_f32 v48, v38, v39
	v_cvt_pk_bf16_f32 v49, v40, v41
	v_add_u32_e32 v174, 0xc6000, v149
	global_store_dwordx4 v174, v[46:49], s[92:93]
	v_pk_mul_f32 v[30:31], v[30:31], v[162:163] op_sel_hi:[1,0]
	v_pk_mul_f32 v[32:33], v[32:33], v[162:163] op_sel_hi:[1,0]
	v_pk_mul_f32 v[22:23], v[22:23], v[162:163] op_sel_hi:[1,0]
	v_pk_mul_f32 v[24:25], v[24:25], v[162:163] op_sel_hi:[1,0]
	v_pk_mul_f32 v[26:27], v[26:27], v[162:163] op_sel_hi:[1,0]
	v_pk_mul_f32 v[28:29], v[28:29], v[162:163] op_sel_hi:[1,0]
	v_pk_mul_f32 v[18:19], v[18:19], v[162:163] op_sel_hi:[1,0]
	v_pk_mul_f32 v[20:21], v[20:21], v[162:163] op_sel_hi:[1,0]
	v_pk_mul_f32 v[166:167], v[30:31], s[20:21]
	v_pk_mul_f32 v[168:169], v[32:33], s[20:21]
	v_pk_mul_f32 v[170:171], v[22:23], s[20:21]
	v_pk_mul_f32 v[172:173], v[24:25], s[20:21]
	v_exp_f32_e32 v166, v166
	v_exp_f32_e32 v167, v167
	v_exp_f32_e32 v168, v168
	v_exp_f32_e32 v169, v169
	v_exp_f32_e32 v170, v170
	v_exp_f32_e32 v171, v171
	v_exp_f32_e32 v172, v172
	v_exp_f32_e32 v173, v173
	v_pk_add_f32 v[166:167], v[166:167], 1.0 op_sel_hi:[1,0]
	v_pk_add_f32 v[168:169], v[168:169], 1.0 op_sel_hi:[1,0]
	v_pk_add_f32 v[170:171], v[170:171], 1.0 op_sel_hi:[1,0]
	v_pk_add_f32 v[172:173], v[172:173], 1.0 op_sel_hi:[1,0]
	v_rcp_f32_e32 v166, v166
	v_rcp_f32_e32 v167, v167
	v_rcp_f32_e32 v168, v168
	v_rcp_f32_e32 v169, v169
	v_rcp_f32_e32 v170, v170
	v_rcp_f32_e32 v171, v171
	v_rcp_f32_e32 v172, v172
	v_rcp_f32_e32 v173, v173
	v_pk_mul_f32 v[30:31], v[30:31], v[26:27]
	v_pk_mul_f32 v[32:33], v[32:33], v[28:29]
	v_pk_mul_f32 v[22:23], v[22:23], v[18:19]
	v_pk_mul_f32 v[24:25], v[24:25], v[20:21]
	v_pk_mul_f32 v[30:31], v[30:31], v[166:167]
	v_pk_mul_f32 v[32:33], v[32:33], v[168:169]
	v_pk_mul_f32 v[22:23], v[22:23], v[170:171]
	v_pk_mul_f32 v[24:25], v[24:25], v[172:173]
	v_cvt_pk_bf16_f32 v30, v30, v31
	v_cvt_pk_bf16_f32 v31, v32, v33
	v_cvt_pk_bf16_f32 v32, v22, v23
	v_cvt_pk_bf16_f32 v33, v24, v25
	v_add_u32_e32 v174, 0xdc000, v149
	global_store_dwordx4 v174, v[30:33], s[92:93]
	v_pk_mul_f32 v[14:15], v[14:15], v[164:165] op_sel_hi:[1,0]
	v_pk_mul_f32 v[16:17], v[16:17], v[164:165] op_sel_hi:[1,0]
	v_pk_mul_f32 v[6:7], v[6:7], v[164:165] op_sel_hi:[1,0]
	v_pk_mul_f32 v[8:9], v[8:9], v[164:165] op_sel_hi:[1,0]
	v_pk_mul_f32 v[10:11], v[10:11], v[164:165] op_sel_hi:[1,0]
	v_pk_mul_f32 v[12:13], v[12:13], v[164:165] op_sel_hi:[1,0]
	v_pk_mul_f32 v[2:3], v[2:3], v[164:165] op_sel_hi:[1,0]
	v_pk_mul_f32 v[4:5], v[4:5], v[164:165] op_sel_hi:[1,0]
	v_pk_mul_f32 v[166:167], v[14:15], s[20:21]
	v_pk_mul_f32 v[168:169], v[16:17], s[20:21]
	v_pk_mul_f32 v[170:171], v[6:7], s[20:21]
	v_pk_mul_f32 v[172:173], v[8:9], s[20:21]
	v_exp_f32_e32 v166, v166
	v_exp_f32_e32 v167, v167
	v_exp_f32_e32 v168, v168
	v_exp_f32_e32 v169, v169
	v_exp_f32_e32 v170, v170
	v_exp_f32_e32 v171, v171
	v_exp_f32_e32 v172, v172
	v_exp_f32_e32 v173, v173
	v_pk_add_f32 v[166:167], v[166:167], 1.0 op_sel_hi:[1,0]
	v_pk_add_f32 v[168:169], v[168:169], 1.0 op_sel_hi:[1,0]
	v_pk_add_f32 v[170:171], v[170:171], 1.0 op_sel_hi:[1,0]
	v_pk_add_f32 v[172:173], v[172:173], 1.0 op_sel_hi:[1,0]
	v_rcp_f32_e32 v166, v166
	v_rcp_f32_e32 v167, v167
	v_rcp_f32_e32 v168, v168
	v_rcp_f32_e32 v169, v169
	v_rcp_f32_e32 v170, v170
	v_rcp_f32_e32 v171, v171
	v_rcp_f32_e32 v172, v172
	v_rcp_f32_e32 v173, v173
	v_pk_mul_f32 v[14:15], v[14:15], v[10:11]
	v_pk_mul_f32 v[16:17], v[16:17], v[12:13]
	v_pk_mul_f32 v[6:7], v[6:7], v[2:3]
	v_pk_mul_f32 v[8:9], v[8:9], v[4:5]
	v_pk_mul_f32 v[14:15], v[14:15], v[166:167]
	v_pk_mul_f32 v[16:17], v[16:17], v[168:169]
	v_pk_mul_f32 v[6:7], v[6:7], v[170:171]
	v_pk_mul_f32 v[8:9], v[8:9], v[172:173]
	v_cvt_pk_bf16_f32 v14, v14, v15
	v_cvt_pk_bf16_f32 v15, v16, v17
	v_cvt_pk_bf16_f32 v16, v6, v7
	v_cvt_pk_bf16_f32 v17, v8, v9
	v_add_u32_e32 v174, 0xf2000, v149
	global_store_dwordx4 v174, v[14:17], s[92:93]
	s_cmp_eq_u32 s17, s35
	s_mov_b64 s[16:17], -1
	s_cbranch_scc1 .LBB0_833
	s_andn2_b64 vcc, exec, s[2:3]
	s_cbranch_vccnz .LBB0_832
	s_barrier
	s_branch .LBB0_832
